# attention K/V tile staging de-serialised: 16 loads issued together with counted waits instead of 16 load-wait-write round trips (on top of v50)
# speedup vs baseline: 1.0117x; 1.0117x over previous
; #define LAS __attribute__((address_space(3)))
; __device__ void attn_item(const bf16_t* __restrict__ QX, const bf16_t* __restrict__ KV, bf16_t* __restrict__ O, int tt, int head, LAS unsigned char* lds) {
;     ...
; #pragma unroll 4
;   for (int it = 0; it < 16; ++it) { const int q = tid + it * 512, m = q >> 5, c = q & 31;
;     *(LAS u32x4*)(lds + m * KS + c * 16) = *(const u32x4*)(KV + (size_t)(mrow0 + m) * 2048 + head * 256 + c * 8); }
;   __syncthreads();
;   const int il = l & 31, h = l >> 5, i16 = l & 15, q4 = i16 >> 2, p4 = i16 & 3, G1 = (l >> 4) & 1;
;   const int row = row0 + w * 32 + il;
;   bf16x8 pf[8][2];
;   float mxp = -3.0e38f, sum = 0.f;
;   const bf16_t* qp = QX + (size_t)row * 1024 + head * 256 + 8 * h;
; #pragma unroll
;   for (int hf = 0; hf < 2; ++hf) {
;     f32x16 sc[4];
; #pragma unroll
;     for (int i = 0; i < 4; ++i) sc[i] = (f32x16){};
.LBB0_982:
	v_readlane_b32 s20, v255, 62
	v_readlane_b32 s12, v255, 61
	s_min_i32 s7, s20, 64
	s_lshl_b32 s22, s12, 8
	s_lshl_b32 s7, s7, 5
	s_ashr_i32 s23, s22, 31
	v_mov_b32_e32 v133, v214
	s_and_b32 s7, s7, 0xffffff00
	s_lshl_b64 s[34:35], s[22:23], 1
	s_add_u32 s12, s14, s34
	v_and_b32_e32 v0, 31, v133
	s_addc_u32 s13, s15, s35
	v_lshlrev_b32_e32 v160, 4, v0
	v_lshl_add_u64 v[128:129], s[12:13], 0, v[160:161]
	v_add_u32_e32 v132, 0, v160
	v_lshrrev_b32_e32 v1, 5, v133
	v_add_u32_e32 v2, s7, v1
	v_ashrrev_i32_e32 v3, 31, v2
	v_lshlrev_b64 v[2:3], 12, v[2:3]
	v_lshl_add_u64 v[2:3], v[128:129], 0, v[2:3]
	v_mad_u32_u24 v6, v1, s59, v132
	s_mov_b64 s[36:37], 0x10000
	v_add_u32_e32 v7, 0x10800, v6
	global_load_dwordx4 v[8:11], v[2:3], off
	v_lshl_add_u64 v[2:3], v[2:3], 0, s[36:37]
	global_load_dwordx4 v[12:15], v[2:3], off
	v_lshl_add_u64 v[2:3], v[2:3], 0, s[36:37]
	global_load_dwordx4 v[16:19], v[2:3], off
	v_lshl_add_u64 v[2:3], v[2:3], 0, s[36:37]
	global_load_dwordx4 v[20:23], v[2:3], off
	v_lshl_add_u64 v[2:3], v[2:3], 0, s[36:37]
	global_load_dwordx4 v[24:27], v[2:3], off
	v_lshl_add_u64 v[2:3], v[2:3], 0, s[36:37]
	global_load_dwordx4 v[28:31], v[2:3], off
	v_lshl_add_u64 v[2:3], v[2:3], 0, s[36:37]
	global_load_dwordx4 v[32:35], v[2:3], off
	v_lshl_add_u64 v[2:3], v[2:3], 0, s[36:37]
	global_load_dwordx4 v[36:39], v[2:3], off
	v_lshl_add_u64 v[2:3], v[2:3], 0, s[36:37]
	global_load_dwordx4 v[40:43], v[2:3], off
	v_lshl_add_u64 v[2:3], v[2:3], 0, s[36:37]
	global_load_dwordx4 v[44:47], v[2:3], off
	v_lshl_add_u64 v[2:3], v[2:3], 0, s[36:37]
	global_load_dwordx4 v[48:51], v[2:3], off
	v_lshl_add_u64 v[2:3], v[2:3], 0, s[36:37]
	global_load_dwordx4 v[52:55], v[2:3], off
	v_lshl_add_u64 v[2:3], v[2:3], 0, s[36:37]
	global_load_dwordx4 v[56:59], v[2:3], off
	v_lshl_add_u64 v[2:3], v[2:3], 0, s[36:37]
	global_load_dwordx4 v[60:63], v[2:3], off
	v_lshl_add_u64 v[2:3], v[2:3], 0, s[36:37]
	global_load_dwordx4 v[64:67], v[2:3], off
	v_lshl_add_u64 v[2:3], v[2:3], 0, s[36:37]
	global_load_dwordx4 v[68:71], v[2:3], off
	s_waitcnt vmcnt(15)
	ds_write_b128 v6, v[8:11]
	s_waitcnt vmcnt(14)
	ds_write_b128 v6, v[12:15] offset:8448
	s_waitcnt vmcnt(13)
	ds_write_b128 v6, v[16:19] offset:16896
	s_waitcnt vmcnt(12)
	ds_write_b128 v6, v[20:23] offset:25344
	s_waitcnt vmcnt(11)
	ds_write_b128 v6, v[24:27] offset:33792
	s_waitcnt vmcnt(10)
	ds_write_b128 v6, v[28:31] offset:42240
	s_waitcnt vmcnt(9)
	ds_write_b128 v6, v[32:35] offset:50688
	s_waitcnt vmcnt(8)
	ds_write_b128 v6, v[36:39] offset:59136
	s_waitcnt vmcnt(7)
	ds_write_b128 v7, v[40:43]
	s_waitcnt vmcnt(6)
	ds_write_b128 v7, v[44:47] offset:8448
	s_waitcnt vmcnt(5)
	ds_write_b128 v7, v[48:51] offset:16896
	s_waitcnt vmcnt(4)
	ds_write_b128 v7, v[52:55] offset:25344
	s_waitcnt vmcnt(3)
	ds_write_b128 v7, v[56:59] offset:33792
	s_waitcnt vmcnt(2)
	ds_write_b128 v7, v[60:63] offset:42240
	s_waitcnt vmcnt(1)
	ds_write_b128 v7, v[64:67] offset:50688
	s_waitcnt vmcnt(0)
	ds_write_b128 v7, v[68:71] offset:59136
	s_movk_i32 s12, 0x2000
	v_ashrrev_i32_e32 v1, 1, v133
	v_and_b32_e32 v1, 0xffffffe0, v1
	v_lshl_add_u32 v1, s20, 8, v1
	v_or_b32_e32 v130, v1, v0
	v_bfe_u32 v136, v133, 5, 1
	v_ashrrev_i32_e32 v131, 31, v130
	v_readlane_b32 s12, v255, 44
	v_mul_u32_u24_e32 v2, 0x210, v0
	v_lshlrev_b32_e32 v160, 4, v136
	v_lshlrev_b64 v[0:1], 11, v[130:131]
	s_add_u32 s12, s12, s34
	v_readlane_b32 s13, v255, 45
	v_or_b32_e32 v0, v0, v160
	s_addc_u32 s13, s13, s35
	v_lshl_add_u64 v[134:135], s[12:13], 0, v[0:1]
	v_mov_b32_e32 v0, 0
	v_add3_u32 v138, v2, v160, 0
	s_mov_b32 s12, 0
	v_mov_b64_e32 v[64:65], v[134:135]
	v_mov_b32_e32 v1, v0
	v_mov_b32_e32 v2, v0
	v_mov_b32_e32 v3, v0
	v_mov_b32_e32 v4, v0
	v_mov_b32_e32 v5, v0
	v_mov_b32_e32 v6, v0
	v_mov_b32_e32 v7, v0
	v_mov_b32_e32 v8, v0
	v_mov_b32_e32 v9, v0
	v_mov_b32_e32 v10, v0
	v_mov_b32_e32 v11, v0
	v_mov_b32_e32 v12, v0
	v_mov_b32_e32 v13, v0
	v_mov_b32_e32 v14, v0
	v_mov_b32_e32 v15, v0
	v_mov_b32_e32 v16, v0
	v_mov_b32_e32 v17, v0
	v_mov_b32_e32 v18, v0
	v_mov_b32_e32 v19, v0
	v_mov_b32_e32 v20, v0
	v_mov_b32_e32 v21, v0
	v_mov_b32_e32 v22, v0
	v_mov_b32_e32 v23, v0
	v_mov_b32_e32 v24, v0
	v_mov_b32_e32 v25, v0
	v_mov_b32_e32 v26, v0
	v_mov_b32_e32 v27, v0
	v_mov_b32_e32 v28, v0
	v_mov_b32_e32 v29, v0
	v_mov_b32_e32 v30, v0
	v_mov_b32_e32 v31, v0
	v_mov_b32_e32 v32, v0
	v_mov_b32_e32 v33, v0
	v_mov_b32_e32 v34, v0
	v_mov_b32_e32 v35, v0
	v_mov_b32_e32 v36, v0
	v_mov_b32_e32 v37, v0
	v_mov_b32_e32 v38, v0
	v_mov_b32_e32 v39, v0
	v_mov_b32_e32 v40, v0
	v_mov_b32_e32 v41, v0
	v_mov_b32_e32 v42, v0
	v_mov_b32_e32 v43, v0
	v_mov_b32_e32 v44, v0
	v_mov_b32_e32 v45, v0
	v_mov_b32_e32 v46, v0
	v_mov_b32_e32 v47, v0
	v_mov_b32_e32 v48, v0
	v_mov_b32_e32 v49, v0
	v_mov_b32_e32 v50, v0
	v_mov_b32_e32 v51, v0
	v_mov_b32_e32 v52, v0
	v_mov_b32_e32 v53, v0
	v_mov_b32_e32 v54, v0
	v_mov_b32_e32 v55, v0
	v_mov_b32_e32 v56, v0
	v_mov_b32_e32 v57, v0
	v_mov_b32_e32 v58, v0
	v_mov_b32_e32 v59, v0
	v_mov_b32_e32 v60, v0
	v_mov_b32_e32 v61, v0
	v_mov_b32_e32 v62, v0
	v_mov_b32_e32 v63, v0
	s_waitcnt lgkmcnt(0)
	s_barrier

; #define LAS __attribute__((address_space(3)))
; __device__ __forceinline__ unsigned cvt_pk_bf16(float lo, float hi) { f32x2 v = {lo, hi}; bf16x2_t b = __builtin_convertvector(v, bf16x2_t); return __builtin_bit_cast(unsigned, b); }
; __device__ __forceinline__ f32x16 mfma32(bf16x8 a, bf16x8 b, f32x16 c) { return __builtin_amdgcn_mfma_f32_32x32x16_bf16(a, b, c, 0, 0, 0); }
; __device__ void attn_item(const bf16_t* __restrict__ QX, const bf16_t* __restrict__ KV, bf16_t* __restrict__ O, int tt, int head, LAS unsigned char* lds) {
;     ...
;     for (int ks = 0; ks < 16; ++ks) {
;       const bf16x8 B = *(const bf16x8*)(qp + 16 * ks);
; #pragma unroll
;       for (int mt = 0; mt < 4; ++mt) sc[mt] = mfma32(*(const LAS bf16x8*)(lds + ((hf * 4 + mt) * 32 + il) * KS + (16 * ks + 8 * h) * 2), B, sc[mt]);
;     }
;     ...
;     for (int mt = 0; mt < 4; ++mt) {
;       u32x4 p0, p1;
; #pragma unroll
;       for (int r = 0; r < 16; r += 2) {
;         const float e0 = __builtin_amdgcn_exp2f((sc[mt][r] - mx) * 1.4426950408889634f), e1 = __builtin_amdgcn_exp2f((sc[mt][r + 1] - mx) * 1.4426950408889634f);
;         sum += e0 + e1; const unsigned pk = cvt_pk_bf16(e0, e1);
;         if (r < 8) p0[r >> 1] = pk; else p1[(r - 8) >> 1] = pk;
;       }
;       pf[hf * 4 + mt][0] = (bf16x8)p0; pf[hf * 4 + mt][1] = (bf16x8)p1;
.LBB0_987:
	global_load_dwordx4 v[142:145], v[134:135], off offset:-64
	v_add_u32_e32 v141, s12, v138
	v_add_u32_e32 v146, 0x10800, v141
	ds_read_b128 v[146:149], v146
	s_addk_i32 s12, 0x80
	s_cmpk_lg_i32 s12, 0x200
	s_waitcnt vmcnt(0) lgkmcnt(0)
	v_mfma_f32_32x32x16_bf16 v[112:127], v[146:149], v[142:145], v[112:127]
	v_add_u32_e32 v146, 0x14a00, v141
	ds_read_b128 v[146:149], v146
	s_waitcnt lgkmcnt(0)
	v_mfma_f32_32x32x16_bf16 v[96:111], v[146:149], v[142:145], v[96:111]
	v_add_u32_e32 v146, 0x18c00, v141
	ds_read_b128 v[146:149], v146
	s_waitcnt lgkmcnt(0)
	v_mfma_f32_32x32x16_bf16 v[80:95], v[146:149], v[142:145], v[80:95]
	v_add_u32_e32 v146, 0x1ce00, v141
	ds_read_b128 v[146:149], v146
	s_waitcnt lgkmcnt(0)
	v_mfma_f32_32x32x16_bf16 v[64:79], v[146:149], v[142:145], v[64:79]
	global_load_dwordx4 v[142:145], v[134:135], off offset:-32
	v_add_u32_e32 v146, 0x10820, v141
	ds_read_b128 v[146:149], v146
	s_waitcnt vmcnt(0) lgkmcnt(0)
	v_mfma_f32_32x32x16_bf16 v[112:127], v[146:149], v[142:145], v[112:127]
	v_add_u32_e32 v146, 0x14a20, v141
	ds_read_b128 v[146:149], v146
	s_waitcnt lgkmcnt(0)
	v_mfma_f32_32x32x16_bf16 v[96:111], v[146:149], v[142:145], v[96:111]
	v_add_u32_e32 v146, 0x18c20, v141
	ds_read_b128 v[146:149], v146
	s_waitcnt lgkmcnt(0)
	v_mfma_f32_32x32x16_bf16 v[80:95], v[146:149], v[142:145], v[80:95]
	v_add_u32_e32 v146, 0x1ce20, v141
	ds_read_b128 v[146:149], v146
	s_waitcnt lgkmcnt(0)
	v_mfma_f32_32x32x16_bf16 v[64:79], v[146:149], v[142:145], v[64:79]
	global_load_dwordx4 v[142:145], v[134:135], off
	v_add_u32_e32 v146, 0x10840, v141
	ds_read_b128 v[146:149], v146
	s_waitcnt vmcnt(0) lgkmcnt(0)
	v_mfma_f32_32x32x16_bf16 v[112:127], v[146:149], v[142:145], v[112:127]
	v_add_u32_e32 v146, 0x14a40, v141
	ds_read_b128 v[146:149], v146
	s_waitcnt lgkmcnt(0)
	v_mfma_f32_32x32x16_bf16 v[96:111], v[146:149], v[142:145], v[96:111]
	v_add_u32_e32 v146, 0x18c40, v141
	ds_read_b128 v[146:149], v146
	s_waitcnt lgkmcnt(0)
	v_mfma_f32_32x32x16_bf16 v[80:95], v[146:149], v[142:145], v[80:95]
	v_add_u32_e32 v146, 0x1ce40, v141
	ds_read_b128 v[146:149], v146
	s_waitcnt lgkmcnt(0)
	v_mfma_f32_32x32x16_bf16 v[64:79], v[146:149], v[142:145], v[64:79]
	global_load_dwordx4 v[142:145], v[134:135], off offset:32
	v_add_u32_e32 v146, 0x10860, v141
	ds_read_b128 v[146:149], v146
	v_lshl_add_u64 v[134:135], v[134:135], 0, s[80:81]
	s_waitcnt vmcnt(0) lgkmcnt(0)
	v_mfma_f32_32x32x16_bf16 v[112:127], v[146:149], v[142:145], v[112:127]
	v_add_u32_e32 v146, 0x14a60, v141
	ds_read_b128 v[146:149], v146
	s_waitcnt lgkmcnt(0)
	v_mfma_f32_32x32x16_bf16 v[96:111], v[146:149], v[142:145], v[96:111]
	v_add_u32_e32 v146, 0x18c60, v141
	ds_read_b128 v[146:149], v146
	v_add_u32_e32 v141, 0x1ce60, v141
	s_waitcnt lgkmcnt(0)
	v_mfma_f32_32x32x16_bf16 v[80:95], v[146:149], v[142:145], v[80:95]
	ds_read_b128 v[146:149], v141
	s_waitcnt lgkmcnt(0)
	v_mfma_f32_32x32x16_bf16 v[64:79], v[146:149], v[142:145], v[64:79]
	s_cbranch_scc1 .LBB0_987
	v_max_f32_e32 v134, v140, v140
	v_max_f32_e32 v135, v139, v139
	v_max_f32_e32 v152, v135, v134
	v_sub_f32_e32 v0, v0, v152
	v_sub_f32_e32 v48, v48, v152
	v_sub_f32_e32 v49, v49, v152
	v_mul_f32_e32 v0, 0x3fb8aa3b, v0
	v_mul_f32_e32 v48, 0x3fb8aa3b, v48
	v_mul_f32_e32 v49, 0x3fb8aa3b, v49
	v_sub_f32_e32 v50, v50, v152
	v_sub_f32_e32 v51, v51, v152
	v_exp_f32_e32 v134, v0
	v_sub_f32_e32 v0, v1, v152
	v_exp_f32_e32 v48, v48
	v_exp_f32_e32 v49, v49
	v_mul_f32_e32 v50, 0x3fb8aa3b, v50
	v_mul_f32_e32 v51, 0x3fb8aa3b, v51
	v_sub_f32_e32 v52, v52, v152
	v_sub_f32_e32 v53, v53, v152
	v_mul_f32_e32 v0, 0x3fb8aa3b, v0
	v_exp_f32_e32 v50, v50
	v_exp_f32_e32 v51, v51
	v_mul_f32_e32 v52, 0x3fb8aa3b, v52
	v_mul_f32_e32 v53, 0x3fb8aa3b, v53
	v_sub_f32_e32 v54, v54, v152
	v_sub_f32_e32 v55, v55, v152
	v_exp_f32_e32 v135, v0
	v_sub_f32_e32 v0, v2, v152
	v_exp_f32_e32 v52, v52
	v_exp_f32_e32 v53, v53
	v_mul_f32_e32 v54, 0x3fb8aa3b, v54
	v_mul_f32_e32 v55, 0x3fb8aa3b, v55
	v_sub_f32_e32 v56, v56, v152
	v_sub_f32_e32 v57, v57, v152
	v_mul_f32_e32 v0, 0x3fb8aa3b, v0
	v_exp_f32_e32 v54, v54
	v_exp_f32_e32 v55, v55
	v_mul_f32_e32 v56, 0x3fb8aa3b, v56
	v_mul_f32_e32 v57, 0x3fb8aa3b, v57
	v_sub_f32_e32 v58, v58, v152
	v_sub_f32_e32 v59, v59, v152
	v_exp_f32_e32 v138, v0
	v_sub_f32_e32 v0, v3, v152
	v_add_f32_e32 v153, v48, v49
	v_exp_f32_e32 v56, v56
	v_exp_f32_e32 v57, v57
	v_mul_f32_e32 v58, 0x3fb8aa3b, v58
	v_mul_f32_e32 v59, 0x3fb8aa3b, v59
	v_sub_f32_e32 v60, v60, v152
	v_sub_f32_e32 v61, v61, v152
	v_mul_f32_e32 v0, 0x3fb8aa3b, v0
	v_add_f32_e32 v154, v50, v51
	v_exp_f32_e32 v58, v58
	v_exp_f32_e32 v59, v59
	v_mul_f32_e32 v60, 0x3fb8aa3b, v60
	v_mul_f32_e32 v61, 0x3fb8aa3b, v61
	v_sub_f32_e32 v62, v62, v152
	v_sub_f32_e32 v63, v63, v152
	v_exp_f32_e32 v139, v0
	v_sub_f32_e32 v0, v4, v152
	v_sub_f32_e32 v4, v8, v152
	v_add_f32_e32 v8, 0, v153
	v_add_f32_e32 v155, v52, v53
	v_exp_f32_e32 v60, v60
	v_exp_f32_e32 v61, v61
	v_mul_f32_e32 v62, 0x3fb8aa3b, v62
	v_mul_f32_e32 v63, 0x3fb8aa3b, v63
	v_sub_f32_e32 v32, v32, v152
	v_sub_f32_e32 v33, v33, v152
	v_add_f32_e32 v8, v154, v8
	v_add_f32_e32 v156, v54, v55
	v_exp_f32_e32 v62, v62
	v_exp_f32_e32 v63, v63
	v_mul_f32_e32 v32, 0x3fb8aa3b, v32
	v_mul_f32_e32 v33, 0x3fb8aa3b, v33
	v_sub_f32_e32 v34, v34, v152
	v_sub_f32_e32 v35, v35, v152
	v_add_f32_e32 v8, v155, v8
	v_add_f32_e32 v157, v56, v57
	v_exp_f32_e32 v32, v32
	v_exp_f32_e32 v33, v33
	v_mul_f32_e32 v34, 0x3fb8aa3b, v34
	v_mul_f32_e32 v35, 0x3fb8aa3b, v35
	v_sub_f32_e32 v36, v36, v152
	v_sub_f32_e32 v37, v37, v152
	v_add_f32_e32 v8, v156, v8
	v_add_f32_e32 v158, v58, v59
	v_exp_f32_e32 v34, v34
	v_exp_f32_e32 v35, v35
	v_mul_f32_e32 v36, 0x3fb8aa3b, v36
; __device__ __forceinline__ unsigned cvt_pk_bf16(float lo, float hi) { f32x2 v = {lo, hi}; bf16x2_t b = __builtin_convertvector(v, bf16x2_t); return __builtin_bit_cast(unsigned, b); }
; __device__ void attn_item(const bf16_t* __restrict__ QX, const bf16_t* __restrict__ KV, bf16_t* __restrict__ O, int tt, int head, LAS unsigned char* lds) {
;     ...
;     float mx = mxp;
; #pragma unroll
;     for (int mt = 0; mt < 4; ++mt)
; #pragma unroll
;       for (int r = 0; r < 16; ++r) mx = fmaxf(mx, sc[mt][r]);
;     mx = fmaxf(mx, __shfl_xor(mx, 32));
;     if (hf == 1) { const float f = __builtin_amdgcn_exp2f((mxp - mx) * 1.4426950408889634f); sum *= f;
; #pragma unroll
;       for (int mt = 0; mt < 4; ++mt) { pf[mt][0] = scale_frag(pf[mt][0], f); pf[mt][1] = scale_frag(pf[mt][1], f); } }
; #pragma unroll
;     for (int mt = 0; mt < 4; ++mt) {
;       u32x4 p0, p1;
; #pragma unroll
;       for (int r = 0; r < 16; r += 2) {
;         const float e0 = __builtin_amdgcn_exp2f((sc[mt][r] - mx) * 1.4426950408889634f), e1 = __builtin_amdgcn_exp2f((sc[mt][r + 1] - mx) * 1.4426950408889634f);
;         sum += e0 + e1; const unsigned pk = cvt_pk_bf16(e0, e1);
;         if (r < 8) p0[r >> 1] = pk; else p1[(r - 8) >> 1] = pk;
;       }
;       pf[hf * 4 + mt][0] = (bf16x8)p0; pf[hf * 4 + mt][1] = (bf16x8)p1;
	v_mul_f32_e32 v37, 0x3fb8aa3b, v37
	v_sub_f32_e32 v38, v38, v152
	v_sub_f32_e32 v39, v39, v152
	v_add_f32_e32 v8, v157, v8
	v_add_f32_e32 v159, v60, v61
	v_exp_f32_e32 v36, v36
	v_exp_f32_e32 v37, v37
	v_mul_f32_e32 v38, 0x3fb8aa3b, v38
	v_mul_f32_e32 v39, 0x3fb8aa3b, v39
	v_sub_f32_e32 v40, v40, v152
	v_sub_f32_e32 v41, v41, v152
	v_add_f32_e32 v8, v158, v8
	v_add_f32_e32 v174, v62, v63
	v_exp_f32_e32 v38, v38
	v_exp_f32_e32 v39, v39
	v_mul_f32_e32 v40, 0x3fb8aa3b, v40
	v_mul_f32_e32 v41, 0x3fb8aa3b, v41
	v_sub_f32_e32 v42, v42, v152
	v_sub_f32_e32 v43, v43, v152
	v_add_f32_e32 v8, v159, v8
	v_add_f32_e32 v175, v32, v33
	v_exp_f32_e32 v40, v40
	v_exp_f32_e32 v41, v41
	v_mul_f32_e32 v42, 0x3fb8aa3b, v42
	v_mul_f32_e32 v43, 0x3fb8aa3b, v43
	v_sub_f32_e32 v44, v44, v152
	v_sub_f32_e32 v45, v45, v152
	v_add_f32_e32 v8, v174, v8
	v_add_f32_e32 v176, v34, v35
	v_exp_f32_e32 v42, v42
	v_exp_f32_e32 v43, v43
	v_mul_f32_e32 v44, 0x3fb8aa3b, v44
	v_mul_f32_e32 v45, 0x3fb8aa3b, v45
	v_sub_f32_e32 v46, v46, v152
	v_sub_f32_e32 v47, v47, v152
	v_add_f32_e32 v8, v175, v8
	v_add_f32_e32 v177, v36, v37
	v_exp_f32_e32 v44, v44
	v_exp_f32_e32 v45, v45
	v_mul_f32_e32 v46, 0x3fb8aa3b, v46
	v_mul_f32_e32 v47, 0x3fb8aa3b, v47
	v_sub_f32_e32 v16, v16, v152
	v_sub_f32_e32 v17, v17, v152
	v_add_f32_e32 v8, v176, v8
	v_add_f32_e32 v178, v38, v39
	v_exp_f32_e32 v46, v46
	v_exp_f32_e32 v47, v47
	v_mul_f32_e32 v16, 0x3fb8aa3b, v16
	v_mul_f32_e32 v17, 0x3fb8aa3b, v17
	v_sub_f32_e32 v18, v18, v152
	v_sub_f32_e32 v19, v19, v152
	v_add_f32_e32 v8, v177, v8
	v_add_f32_e32 v179, v40, v41
	v_exp_f32_e32 v16, v16
	v_exp_f32_e32 v17, v17
	v_mul_f32_e32 v18, 0x3fb8aa3b, v18
	v_mul_f32_e32 v19, 0x3fb8aa3b, v19
	v_sub_f32_e32 v20, v20, v152
	v_sub_f32_e32 v21, v21, v152
	v_add_f32_e32 v8, v178, v8
	v_add_f32_e32 v180, v42, v43
	v_exp_f32_e32 v18, v18
	v_exp_f32_e32 v19, v19
	v_mul_f32_e32 v20, 0x3fb8aa3b, v20
	v_mul_f32_e32 v21, 0x3fb8aa3b, v21
	v_sub_f32_e32 v22, v22, v152
	v_sub_f32_e32 v23, v23, v152
	v_add_f32_e32 v8, v179, v8
	v_add_f32_e32 v181, v44, v45
	v_exp_f32_e32 v20, v20
	v_exp_f32_e32 v21, v21
	v_mul_f32_e32 v22, 0x3fb8aa3b, v22
	v_mul_f32_e32 v23, 0x3fb8aa3b, v23
	v_sub_f32_e32 v24, v24, v152
	v_sub_f32_e32 v25, v25, v152
	v_add_f32_e32 v8, v180, v8
	v_add_f32_e32 v182, v46, v47
	v_exp_f32_e32 v22, v22
	v_exp_f32_e32 v23, v23
	v_mul_f32_e32 v24, 0x3fb8aa3b, v24
	v_mul_f32_e32 v25, 0x3fb8aa3b, v25
	v_sub_f32_e32 v26, v26, v152
	v_sub_f32_e32 v27, v27, v152
	v_add_f32_e32 v8, v181, v8
	v_add_f32_e32 v183, v16, v17
	v_exp_f32_e32 v24, v24
	v_exp_f32_e32 v25, v25
	v_mul_f32_e32 v26, 0x3fb8aa3b, v26
	v_mul_f32_e32 v27, 0x3fb8aa3b, v27
	v_sub_f32_e32 v28, v28, v152
	v_sub_f32_e32 v29, v29, v152
	v_add_f32_e32 v8, v182, v8
	v_add_f32_e32 v184, v18, v19
	v_exp_f32_e32 v26, v26
	v_exp_f32_e32 v27, v27
	v_mul_f32_e32 v28, 0x3fb8aa3b, v28
	v_mul_f32_e32 v29, 0x3fb8aa3b, v29
	v_sub_f32_e32 v30, v30, v152
	v_sub_f32_e32 v31, v31, v152
	v_mul_f32_e32 v0, 0x3fb8aa3b, v0
	v_add_f32_e32 v8, v183, v8
	v_add_f32_e32 v185, v20, v21
	v_exp_f32_e32 v28, v28
	v_exp_f32_e32 v29, v29
	v_mul_f32_e32 v30, 0x3fb8aa3b, v30
	v_mul_f32_e32 v31, 0x3fb8aa3b, v31
	v_exp_f32_e32 v140, v0
	v_sub_f32_e32 v0, v5, v152
	v_add_f32_e32 v8, v184, v8
	v_add_f32_e32 v186, v22, v23
	v_exp_f32_e32 v30, v30
	v_exp_f32_e32 v31, v31
	v_mul_f32_e32 v0, 0x3fb8aa3b, v0
	v_add_f32_e32 v8, v185, v8
	v_add_f32_e32 v187, v24, v25
	v_exp_f32_e32 v141, v0
	v_sub_f32_e32 v0, v6, v152
	v_add_f32_e32 v8, v186, v8
	v_add_f32_e32 v188, v26, v27
	v_mul_f32_e32 v0, 0x3fb8aa3b, v0
	v_add_f32_e32 v8, v187, v8
	v_add_f32_e32 v189, v28, v29
	v_exp_f32_e32 v142, v0
	v_sub_f32_e32 v0, v7, v152
	v_add_f32_e32 v8, v188, v8
	v_add_f32_e32 v190, v30, v31
	v_mul_f32_e32 v0, 0x3fb8aa3b, v0
	v_add_f32_e32 v8, v189, v8
	v_exp_f32_e32 v143, v0
	v_add_f32_e32 v0, v134, v135
	v_add_f32_e32 v8, v190, v8
	v_add_f32_e32 v1, v138, v139
	v_add_f32_e32 v0, v0, v8
	v_add_f32_e32 v0, v1, v0
	v_max3_f32 v1, v152, v112, v113
	v_max3_f32 v1, v1, v114, v115
	v_max3_f32 v1, v1, v116, v117
	v_max3_f32 v1, v1, v118, v119
	v_max3_f32 v1, v1, v120, v121
	v_max3_f32 v1, v1, v122, v123
	v_max3_f32 v1, v1, v124, v125
	v_max3_f32 v1, v1, v126, v127
	v_max3_f32 v1, v1, v96, v97
	v_max3_f32 v1, v1, v98, v99
	v_max3_f32 v1, v1, v100, v101
	v_max3_f32 v1, v1, v102, v103
	v_max3_f32 v1, v1, v104, v105
	v_max3_f32 v1, v1, v106, v107
	v_max3_f32 v1, v1, v108, v109
	v_max3_f32 v1, v1, v110, v111
	v_max3_f32 v1, v1, v80, v81
	v_max3_f32 v1, v1, v82, v83
	v_max3_f32 v1, v1, v84, v85
	v_mul_f32_e32 v4, 0x3fb8aa3b, v4
	v_max3_f32 v1, v1, v86, v87
	v_exp_f32_e32 v144, v4
	v_sub_f32_e32 v4, v9, v152
	v_max3_f32 v1, v1, v88, v89
	v_mul_f32_e32 v4, 0x3fb8aa3b, v4
	v_max3_f32 v1, v1, v90, v91
	v_exp_f32_e32 v145, v4
	v_sub_f32_e32 v4, v10, v152
	v_max3_f32 v1, v1, v92, v93
	v_mul_f32_e32 v4, 0x3fb8aa3b, v4
	v_max3_f32 v1, v1, v94, v95
	v_exp_f32_e32 v146, v4
	v_sub_f32_e32 v4, v11, v152
	v_max3_f32 v1, v1, v64, v65
	v_mul_f32_e32 v4, 0x3fb8aa3b, v4
	v_max3_f32 v1, v1, v66, v67
	v_exp_f32_e32 v147, v4
	v_sub_f32_e32 v4, v12, v152
	v_max3_f32 v1, v1, v68, v69
	v_mul_f32_e32 v4, 0x3fb8aa3b, v4
	v_max3_f32 v1, v1, v70, v71
	v_exp_f32_e32 v148, v4
	v_sub_f32_e32 v4, v13, v152
	v_max3_f32 v1, v1, v72, v73
	v_mul_f32_e32 v4, 0x3fb8aa3b, v4
	v_max3_f32 v1, v1, v74, v75
	v_exp_f32_e32 v149, v4
	v_sub_f32_e32 v4, v14, v152
	v_max3_f32 v1, v1, v76, v77
	v_add_f32_e32 v2, v140, v141
	v_mul_f32_e32 v4, 0x3fb8aa3b, v4
	v_max3_f32 v1, v1, v78, v79
	v_exp_f32_e32 v150, v4
	v_sub_f32_e32 v4, v15, v152
	v_add_f32_e32 v0, v2, v0
	ds_bpermute_b32 v2, v137, v1
	v_add_f32_e32 v3, v142, v143
	v_mul_f32_e32 v4, 0x3fb8aa3b, v4
	v_exp_f32_e32 v151, v4
	v_add_f32_e32 v4, v144, v145
	v_add_f32_e32 v0, v3, v0
	v_add_f32_e32 v5, v146, v147
	v_add_f32_e32 v0, v4, v0
	v_add_f32_e32 v6, v148, v149
	v_add_f32_e32 v0, v5, v0
	v_add_f32_e32 v5, v6, v0
	s_waitcnt lgkmcnt(0)
; __device__ __forceinline__ unsigned cvt_pk_bf16(float lo, float hi) { f32x2 v = {lo, hi}; bf16x2_t b = __builtin_convertvector(v, bf16x2_t); return __builtin_bit_cast(unsigned, b); }
; __device__ void attn_item(const bf16_t* __restrict__ QX, const bf16_t* __restrict__ KV, bf16_t* __restrict__ O, int tt, int head, LAS unsigned char* lds) {
;     ...
;     mx = fmaxf(mx, __shfl_xor(mx, 32));
;     if (hf == 1) { const float f = __builtin_amdgcn_exp2f((mxp - mx) * 1.4426950408889634f); sum *= f;
; #pragma unroll
;       for (int mt = 0; mt < 4; ++mt) { pf[mt][0] = scale_frag(pf[mt][0], f); pf[mt][1] = scale_frag(pf[mt][1], f); } }
; #pragma unroll
;     for (int mt = 0; mt < 4; ++mt) {
;       u32x4 p0, p1;
; #pragma unroll
;       for (int r = 0; r < 16; r += 2) {
;         const float e0 = __builtin_amdgcn_exp2f((sc[mt][r] - mx) * 1.4426950408889634f), e1 = __builtin_amdgcn_exp2f((sc[mt][r + 1] - mx) * 1.4426950408889634f);
;         sum += e0 + e1; const unsigned pk = cvt_pk_bf16(e0, e1);
;         if (r < 8) p0[r >> 1] = pk; else p1[(r - 8) >> 1] = pk;
;       }
;       pf[hf * 4 + mt][0] = (bf16x8)p0; pf[hf * 4 + mt][1] = (bf16x8)p1;
	v_max_f32_e32 v0, v2, v2
	v_max_f32_e32 v182, v1, v0
	v_sub_f32_e32 v1, v112, v182
	v_sub_f32_e32 v2, v113, v182
	v_sub_f32_e32 v0, v152, v182
	v_mul_f32_e32 v1, 0x3fb8aa3b, v1
	v_mul_f32_e32 v2, 0x3fb8aa3b, v2
	v_mul_f32_e32 v0, 0x3fb8aa3b, v0
	v_exp_f32_e32 v1, v1
	v_exp_f32_e32 v2, v2
	v_exp_f32_e32 v0, v0
	v_add_f32_e32 v7, v150, v151
	v_sub_f32_e32 v3, v114, v182
	v_sub_f32_e32 v4, v115, v182
	v_add_f32_e32 v5, v7, v5
	v_add_f32_e32 v9, v1, v2
	v_mul_f32_e32 v3, 0x3fb8aa3b, v3
	v_mul_f32_e32 v4, 0x3fb8aa3b, v4
	v_fmac_f32_e32 v9, v5, v0
	v_sub_f32_e32 v5, v116, v182
	v_sub_f32_e32 v6, v117, v182
	v_exp_f32_e32 v3, v3
	v_exp_f32_e32 v4, v4
	v_mul_f32_e32 v5, 0x3fb8aa3b, v5
	v_mul_f32_e32 v6, 0x3fb8aa3b, v6
	v_exp_f32_e32 v5, v5
	v_exp_f32_e32 v6, v6
	v_add_f32_e32 v10, v3, v4
	v_sub_f32_e32 v7, v118, v182
	v_sub_f32_e32 v8, v119, v182
	v_add_f32_e32 v9, v10, v9
	v_add_f32_e32 v10, v5, v6
	v_mul_f32_e32 v7, 0x3fb8aa3b, v7
	v_mul_f32_e32 v8, 0x3fb8aa3b, v8
	v_add_f32_e32 v13, v10, v9
	v_sub_f32_e32 v9, v120, v182
	v_sub_f32_e32 v10, v121, v182
	v_exp_f32_e32 v7, v7
	v_exp_f32_e32 v8, v8
	v_mul_f32_e32 v9, 0x3fb8aa3b, v9
	v_mul_f32_e32 v10, 0x3fb8aa3b, v10
	v_exp_f32_e32 v9, v9
	v_exp_f32_e32 v10, v10
	v_add_f32_e32 v14, v7, v8
	v_sub_f32_e32 v11, v122, v182
	v_sub_f32_e32 v12, v123, v182
	v_add_f32_e32 v13, v14, v13
	v_add_f32_e32 v14, v9, v10
	v_mul_f32_e32 v11, 0x3fb8aa3b, v11
	v_mul_f32_e32 v12, 0x3fb8aa3b, v12
	v_add_f32_e32 v113, v14, v13
	v_sub_f32_e32 v13, v124, v182
	v_sub_f32_e32 v14, v125, v182
	v_exp_f32_e32 v11, v11
	v_exp_f32_e32 v12, v12
	v_mul_f32_e32 v13, 0x3fb8aa3b, v13
	v_mul_f32_e32 v14, 0x3fb8aa3b, v14
	v_exp_f32_e32 v13, v13
	v_exp_f32_e32 v14, v14
	v_add_f32_e32 v114, v11, v12
	v_sub_f32_e32 v96, v96, v182
	v_sub_f32_e32 v15, v126, v182
	v_sub_f32_e32 v112, v127, v182
	v_add_f32_e32 v113, v114, v113
	v_add_f32_e32 v114, v13, v14
	v_mul_f32_e32 v96, 0x3fb8aa3b, v96
	v_mul_f32_e32 v15, 0x3fb8aa3b, v15
	v_mul_f32_e32 v112, 0x3fb8aa3b, v112
	v_add_f32_e32 v117, v114, v113
	v_exp_f32_e32 v113, v96
	v_sub_f32_e32 v96, v97, v182
	v_exp_f32_e32 v15, v15
	v_exp_f32_e32 v112, v112
	v_mul_f32_e32 v96, 0x3fb8aa3b, v96
	v_exp_f32_e32 v114, v96
	v_sub_f32_e32 v96, v98, v182
	v_mul_f32_e32 v96, 0x3fb8aa3b, v96
	v_exp_f32_e32 v115, v96
	v_sub_f32_e32 v96, v99, v182
	v_sub_f32_e32 v98, v100, v182
	v_add_f32_e32 v118, v15, v112
	v_mul_f32_e32 v96, 0x3fb8aa3b, v96
	v_mul_f32_e32 v98, 0x3fb8aa3b, v98
	v_exp_f32_e32 v116, v96
	v_add_f32_e32 v96, v118, v117
	v_exp_f32_e32 v117, v98
	v_sub_f32_e32 v98, v101, v182
	v_mul_f32_e32 v98, 0x3fb8aa3b, v98
	v_exp_f32_e32 v118, v98
	v_sub_f32_e32 v98, v102, v182
	v_sub_f32_e32 v80, v80, v182
	v_mul_f32_e32 v98, 0x3fb8aa3b, v98
	v_mul_f32_e32 v80, 0x3fb8aa3b, v80
	v_exp_f32_e32 v119, v98
	v_sub_f32_e32 v98, v103, v182
	v_exp_f32_e32 v152, v80
	v_sub_f32_e32 v80, v81, v182
	v_mul_f32_e32 v98, 0x3fb8aa3b, v98
	v_mul_f32_e32 v80, 0x3fb8aa3b, v80
	v_exp_f32_e32 v120, v98
	v_sub_f32_e32 v98, v104, v182
	v_exp_f32_e32 v153, v80
	v_sub_f32_e32 v80, v82, v182
	v_sub_f32_e32 v82, v84, v182
	v_mul_f32_e32 v98, 0x3fb8aa3b, v98
	v_mul_f32_e32 v82, 0x3fb8aa3b, v82
	v_exp_f32_e32 v121, v98
	v_sub_f32_e32 v98, v105, v182
	v_exp_f32_e32 v156, v82
	v_sub_f32_e32 v82, v85, v182
	v_mul_f32_e32 v98, 0x3fb8aa3b, v98
	v_mul_f32_e32 v82, 0x3fb8aa3b, v82
	v_exp_f32_e32 v122, v98
	v_sub_f32_e32 v98, v106, v182
	v_exp_f32_e32 v157, v82
	v_sub_f32_e32 v82, v86, v182
	v_sub_f32_e32 v64, v64, v182
	v_mul_f32_e32 v98, 0x3fb8aa3b, v98
	v_mul_f32_e32 v82, 0x3fb8aa3b, v82
	v_mul_f32_e32 v64, 0x3fb8aa3b, v64
	v_exp_f32_e32 v123, v98
	v_sub_f32_e32 v98, v107, v182
	v_exp_f32_e32 v158, v82
	v_sub_f32_e32 v82, v87, v182
	v_exp_f32_e32 v183, v64
	v_sub_f32_e32 v64, v65, v182
	v_mul_f32_e32 v98, 0x3fb8aa3b, v98
	v_mul_f32_e32 v82, 0x3fb8aa3b, v82
	v_mul_f32_e32 v64, 0x3fb8aa3b, v64
	v_exp_f32_e32 v124, v98
	v_sub_f32_e32 v98, v108, v182
	v_exp_f32_e32 v159, v82
	v_sub_f32_e32 v82, v88, v182
	v_exp_f32_e32 v184, v64
	v_sub_f32_e32 v64, v66, v182
	v_sub_f32_e32 v66, v68, v182
	v_mul_f32_e32 v98, 0x3fb8aa3b, v98
	v_mul_f32_e32 v82, 0x3fb8aa3b, v82
	v_mul_f32_e32 v66, 0x3fb8aa3b, v66
	v_exp_f32_e32 v125, v98
	v_sub_f32_e32 v98, v109, v182
	v_exp_f32_e32 v174, v82
	v_sub_f32_e32 v82, v89, v182
	v_exp_f32_e32 v187, v66
	v_sub_f32_e32 v66, v69, v182
	v_mul_f32_e32 v98, 0x3fb8aa3b, v98
	v_mul_f32_e32 v82, 0x3fb8aa3b, v82
	v_mul_f32_e32 v66, 0x3fb8aa3b, v66
	v_exp_f32_e32 v126, v98
	v_sub_f32_e32 v98, v110, v182
	v_exp_f32_e32 v175, v82
	v_sub_f32_e32 v82, v90, v182
	v_exp_f32_e32 v188, v66
	v_sub_f32_e32 v66, v70, v182
	v_add_f32_e32 v97, v113, v114
	v_mul_f32_e32 v98, 0x3fb8aa3b, v98
	v_mul_f32_e32 v82, 0x3fb8aa3b, v82
	v_mul_f32_e32 v66, 0x3fb8aa3b, v66
	v_add_f32_e32 v96, v97, v96
	v_add_f32_e32 v97, v115, v116
	v_exp_f32_e32 v127, v98
	v_sub_f32_e32 v98, v111, v182
	v_exp_f32_e32 v176, v82
	v_sub_f32_e32 v82, v91, v182
	v_exp_f32_e32 v189, v66
	v_sub_f32_e32 v66, v71, v182
	v_add_f32_e32 v96, v97, v96
	v_add_f32_e32 v97, v117, v118
	v_mul_f32_e32 v98, 0x3fb8aa3b, v98
	v_mul_f32_e32 v80, 0x3fb8aa3b, v80
	v_mul_f32_e32 v82, 0x3fb8aa3b, v82
	v_mul_f32_e32 v66, 0x3fb8aa3b, v66
	v_add_f32_e32 v96, v97, v96
	v_add_f32_e32 v97, v119, v120
	v_exp_f32_e32 v111, v98
	v_exp_f32_e32 v154, v80
	v_sub_f32_e32 v80, v83, v182
	v_exp_f32_e32 v177, v82
	v_sub_f32_e32 v82, v92, v182
	v_exp_f32_e32 v190, v66
	v_sub_f32_e32 v66, v72, v182
	v_add_f32_e32 v96, v97, v96
	v_add_f32_e32 v97, v121, v122
	v_mul_f32_e32 v80, 0x3fb8aa3b, v80
	v_mul_f32_e32 v82, 0x3fb8aa3b, v82
	v_mul_f32_e32 v66, 0x3fb8aa3b, v66
	v_add_f32_e32 v96, v97, v96
	v_add_f32_e32 v97, v123, v124
; #define LAS __attribute__((address_space(3)))
; __device__ __forceinline__ unsigned cvt_pk_bf16(float lo, float hi) { f32x2 v = {lo, hi}; bf16x2_t b = __builtin_convertvector(v, bf16x2_t); return __builtin_bit_cast(unsigned, b); }
; __device__ void attn_item(const bf16_t* __restrict__ QX, const bf16_t* __restrict__ KV, bf16_t* __restrict__ O, int tt, int head, LAS unsigned char* lds) {
;     ...
;         const float e0 = __builtin_amdgcn_exp2f((sc[mt][r] - mx) * 1.4426950408889634f), e1 = __builtin_amdgcn_exp2f((sc[mt][r + 1] - mx) * 1.4426950408889634f);
;         sum += e0 + e1; const unsigned pk = cvt_pk_bf16(e0, e1);
;         if (r < 8) p0[r >> 1] = pk; else p1[(r - 8) >> 1] = pk;
;       }
;       pf[hf * 4 + mt][0] = (bf16x8)p0; pf[hf * 4 + mt][1] = (bf16x8)p1;
;     }
;     mxp = mx;
;   }
;   sum += __shfl_xor(sum, 32);
;   const float inv = __builtin_amdgcn_rcpf(sum);
;   __builtin_amdgcn_sched_barrier(0);
;   __syncthreads();
;   __builtin_amdgcn_sched_barrier(0);
; #pragma unroll 4
;   for (int it = 0; it < 16; ++it) { const int q = tid + it * 512, m = q >> 5, c = q & 31;
;     *(LAS u32x4*)(lds + m * VS + c * 16) = *(const u32x4*)(KV + (size_t)(mrow0 + m) * 2048 + 1024 + head * 256 + c * 8); }
	v_exp_f32_e32 v155, v80
	v_exp_f32_e32 v178, v82
	v_sub_f32_e32 v82, v93, v182
	v_exp_f32_e32 v191, v66
	v_sub_f32_e32 v66, v73, v182
	v_add_f32_e32 v96, v97, v96
	v_add_f32_e32 v97, v125, v126
	v_mul_f32_e32 v82, 0x3fb8aa3b, v82
	v_mul_f32_e32 v66, 0x3fb8aa3b, v66
	v_add_f32_e32 v96, v97, v96
	v_add_f32_e32 v97, v127, v111
	v_exp_f32_e32 v179, v82
	v_sub_f32_e32 v82, v94, v182
	v_exp_f32_e32 v192, v66
	v_sub_f32_e32 v66, v74, v182
	v_add_f32_e32 v80, v97, v96
	v_add_f32_e32 v81, v152, v153
	v_mul_f32_e32 v82, 0x3fb8aa3b, v82
	v_mul_f32_e32 v66, 0x3fb8aa3b, v66
	v_add_f32_e32 v80, v81, v80
	v_add_f32_e32 v81, v154, v155
	v_exp_f32_e32 v180, v82
	v_sub_f32_e32 v82, v95, v182
	v_exp_f32_e32 v193, v66
	v_sub_f32_e32 v66, v75, v182
	v_add_f32_e32 v80, v81, v80
	v_add_f32_e32 v81, v156, v157
	v_mul_f32_e32 v82, 0x3fb8aa3b, v82
	v_mul_f32_e32 v64, 0x3fb8aa3b, v64
	v_mul_f32_e32 v66, 0x3fb8aa3b, v66
	v_add_f32_e32 v80, v81, v80
	v_add_f32_e32 v81, v158, v159
	v_exp_f32_e32 v181, v82
	v_exp_f32_e32 v185, v64
	v_sub_f32_e32 v64, v67, v182
	v_exp_f32_e32 v194, v66
	v_sub_f32_e32 v66, v76, v182
	v_add_f32_e32 v80, v81, v80
	v_add_f32_e32 v81, v174, v175
	v_mul_f32_e32 v64, 0x3fb8aa3b, v64
	v_mul_f32_e32 v66, 0x3fb8aa3b, v66
	v_add_f32_e32 v80, v81, v80
	v_add_f32_e32 v81, v176, v177
	v_exp_f32_e32 v186, v64
	v_exp_f32_e32 v195, v66
	v_sub_f32_e32 v66, v77, v182
	v_add_f32_e32 v80, v81, v80
	v_add_f32_e32 v81, v178, v179
	v_mul_f32_e32 v66, 0x3fb8aa3b, v66
	v_add_f32_e32 v80, v81, v80
	v_add_f32_e32 v81, v180, v181
	v_exp_f32_e32 v196, v66
	v_sub_f32_e32 v66, v78, v182
	v_add_f32_e32 v64, v81, v80
	v_add_f32_e32 v65, v183, v184
	v_mul_f32_e32 v66, 0x3fb8aa3b, v66
	v_add_f32_e32 v64, v65, v64
	v_add_f32_e32 v65, v185, v186
	v_exp_f32_e32 v197, v66
	v_sub_f32_e32 v66, v79, v182
	v_add_f32_e32 v64, v65, v64
	v_add_f32_e32 v65, v187, v188
	v_mul_f32_e32 v66, 0x3fb8aa3b, v66
	v_add_f32_e32 v64, v65, v64
	v_add_f32_e32 v65, v189, v190
	v_exp_f32_e32 v198, v66
	v_add_f32_e32 v64, v65, v64
	v_add_f32_e32 v65, v191, v192
	v_add_f32_e32 v64, v65, v64
	v_add_f32_e32 v65, v193, v194
	v_add_f32_e32 v64, v65, v64
	v_add_f32_e32 v65, v195, v196
	v_add_f32_e32 v64, v65, v64
	v_add_f32_e32 v65, v197, v198
	v_add_f32_e32 v182, v65, v64
	ds_bpermute_b32 v137, v137, v182
	s_waitcnt lgkmcnt(0)
	s_barrier
	v_lshrrev_b32_e32 v108, 5, v133
	v_add_u32_e32 v68, s7, v108
	v_ashrrev_i32_e32 v69, 31, v68
	v_lshlrev_b64 v[68:69], 12, v[68:69]
	v_lshl_add_u64 v[68:69], v[128:129], 0, v[68:69]
	v_mad_u32_u24 v70, v108, s54, v132
	s_mov_b64 s[34:35], 0x10000
	v_add_u32_e32 v71, 0x12000, v70
	global_load_dwordx4 v[64:67], v[68:69], off offset:2048
	v_lshl_add_u64 v[68:69], v[68:69], 0, s[34:35]
	global_load_dwordx4 v[72:75], v[68:69], off offset:2048
	v_lshl_add_u64 v[68:69], v[68:69], 0, s[34:35]
	global_load_dwordx4 v[76:79], v[68:69], off offset:2048
	v_lshl_add_u64 v[68:69], v[68:69], 0, s[34:35]
	global_load_dwordx4 v[80:83], v[68:69], off offset:2048
	v_lshl_add_u64 v[68:69], v[68:69], 0, s[34:35]
	global_load_dwordx4 v[84:87], v[68:69], off offset:2048
	v_lshl_add_u64 v[68:69], v[68:69], 0, s[34:35]
	global_load_dwordx4 v[88:91], v[68:69], off offset:2048
	v_lshl_add_u64 v[68:69], v[68:69], 0, s[34:35]
	global_load_dwordx4 v[92:95], v[68:69], off offset:2048
	v_lshl_add_u64 v[68:69], v[68:69], 0, s[34:35]
	global_load_dwordx4 v[96:99], v[68:69], off offset:2048
	v_lshl_add_u64 v[68:69], v[68:69], 0, s[34:35]
	global_load_dwordx4 v[100:103], v[68:69], off offset:2048
	v_lshl_add_u64 v[68:69], v[68:69], 0, s[34:35]
	global_load_dwordx4 v[104:107], v[68:69], off offset:2048
	v_lshl_add_u64 v[68:69], v[68:69], 0, s[34:35]
	global_load_dwordx4 v[200:203], v[68:69], off offset:2048
	v_lshl_add_u64 v[68:69], v[68:69], 0, s[34:35]
	global_load_dwordx4 v[204:207], v[68:69], off offset:2048
	v_lshl_add_u64 v[68:69], v[68:69], 0, s[34:35]
	global_load_dwordx4 v[208:211], v[68:69], off offset:2048
	v_lshl_add_u64 v[68:69], v[68:69], 0, s[34:35]
	global_load_dwordx4 v[232:235], v[68:69], off offset:2048
	v_lshl_add_u64 v[68:69], v[68:69], 0, s[34:35]
	global_load_dwordx4 v[236:239], v[68:69], off offset:2048
	v_lshl_add_u64 v[68:69], v[68:69], 0, s[34:35]
	global_load_dwordx4 v[240:243], v[68:69], off offset:2048
	s_waitcnt vmcnt(15)
	ds_write_b128 v70, v[64:67]
	s_waitcnt vmcnt(14)
	ds_write_b128 v70, v[72:75] offset:9216
	s_waitcnt vmcnt(13)
	ds_write_b128 v70, v[76:79] offset:18432
	s_waitcnt vmcnt(12)
	ds_write_b128 v70, v[80:83] offset:27648
	s_waitcnt vmcnt(11)
	ds_write_b128 v70, v[84:87] offset:36864
	s_waitcnt vmcnt(10)
	ds_write_b128 v70, v[88:91] offset:46080
	s_waitcnt vmcnt(9)
	ds_write_b128 v70, v[92:95] offset:55296
	s_waitcnt vmcnt(8)
	ds_write_b128 v70, v[96:99] offset:64512
	s_waitcnt vmcnt(7)
	ds_write_b128 v71, v[100:103]
	s_waitcnt vmcnt(6)
	ds_write_b128 v71, v[104:107] offset:9216
	s_waitcnt vmcnt(5)
	ds_write_b128 v71, v[200:203] offset:18432
	s_waitcnt vmcnt(4)
	ds_write_b128 v71, v[204:207] offset:27648
	s_waitcnt vmcnt(3)
	ds_write_b128 v71, v[208:211] offset:36864
	s_waitcnt vmcnt(2)
	ds_write_b128 v71, v[232:235] offset:46080
	s_waitcnt vmcnt(1)
	ds_write_b128 v71, v[236:239] offset:55296
	s_waitcnt vmcnt(0)
; __device__ __forceinline__ unsigned cvt_pk_bf16(float lo, float hi) { f32x2 v = {lo, hi}; bf16x2_t b = __builtin_convertvector(v, bf16x2_t); return __builtin_bit_cast(unsigned, b); }
; __device__ void attn_item(const bf16_t* __restrict__ QX, const bf16_t* __restrict__ KV, bf16_t* __restrict__ O, int tt, int head, LAS unsigned char* lds) {
;     ...
;     if (hf == 1) { const float f = __builtin_amdgcn_exp2f((mxp - mx) * 1.4426950408889634f); sum *= f;
; #pragma unroll
;       for (int mt = 0; mt < 4; ++mt) { pf[mt][0] = scale_frag(pf[mt][0], f); pf[mt][1] = scale_frag(pf[mt][1], f); } }
; #pragma unroll
;     for (int mt = 0; mt < 4; ++mt) {
;       u32x4 p0, p1;
; #pragma unroll
;       for (int r = 0; r < 16; r += 2) {
;         const float e0 = __builtin_amdgcn_exp2f((sc[mt][r] - mx) * 1.4426950408889634f), e1 = __builtin_amdgcn_exp2f((sc[mt][r + 1] - mx) * 1.4426950408889634f);
;         sum += e0 + e1; const unsigned pk = cvt_pk_bf16(e0, e1);
;         if (r < 8) p0[r >> 1] = pk; else p1[(r - 8) >> 1] = pk;
;       }
;       pf[hf * 4 + mt][0] = (bf16x8)p0; pf[hf * 4 + mt][1] = (bf16x8)p1;
	ds_write_b128 v71, v[240:243] offset:64512
	s_movk_i32 s12, 0x2000
	v_cvt_pk_bf16_f32 v48, v48, v49
	v_cvt_pk_bf16_f32 v32, v32, v33
	v_cvt_pk_bf16_f32 v33, v34, v35
	v_cvt_pk_bf16_f32 v34, v36, v37
	v_cvt_pk_bf16_f32 v36, v40, v41
	v_cvt_pk_bf16_f32 v40, v16, v17
	v_lshlrev_b32_e32 v16, 16, v48
	v_and_b32_e32 v17, 0xffff0000, v48
	v_cvt_pk_bf16_f32 v49, v50, v51
	v_pk_mul_f32 v[16:17], v[0:1], v[16:17] op_sel_hi:[0,1]
	v_cvt_pk_bf16_f32 v64, v16, v17
	v_lshlrev_b32_e32 v16, 16, v49
	v_and_b32_e32 v17, 0xffff0000, v49
	v_cvt_pk_bf16_f32 v50, v52, v53
	v_pk_mul_f32 v[16:17], v[0:1], v[16:17] op_sel_hi:[0,1]
	v_cvt_pk_bf16_f32 v65, v16, v17
	v_lshlrev_b32_e32 v16, 16, v50
	v_and_b32_e32 v17, 0xffff0000, v50
	v_cvt_pk_bf16_f32 v51, v54, v55
	v_pk_mul_f32 v[16:17], v[0:1], v[16:17] op_sel_hi:[0,1]
	v_cvt_pk_bf16_f32 v66, v16, v17
	v_lshlrev_b32_e32 v16, 16, v51
	v_and_b32_e32 v17, 0xffff0000, v51
	v_cvt_pk_bf16_f32 v52, v56, v57
	v_pk_mul_f32 v[16:17], v[0:1], v[16:17] op_sel_hi:[0,1]
	v_cvt_pk_bf16_f32 v67, v16, v17
	v_lshlrev_b32_e32 v16, 16, v52
	v_and_b32_e32 v17, 0xffff0000, v52
	v_cvt_pk_bf16_f32 v53, v58, v59
	v_pk_mul_f32 v[16:17], v[0:1], v[16:17] op_sel_hi:[0,1]
	v_cvt_pk_bf16_f32 v68, v16, v17
	v_lshlrev_b32_e32 v16, 16, v53
	v_and_b32_e32 v17, 0xffff0000, v53
	v_cvt_pk_bf16_f32 v54, v60, v61
	v_pk_mul_f32 v[16:17], v[0:1], v[16:17] op_sel_hi:[0,1]
	v_cvt_pk_bf16_f32 v69, v16, v17
	v_lshlrev_b32_e32 v16, 16, v54
	v_and_b32_e32 v17, 0xffff0000, v54
	v_cvt_pk_bf16_f32 v55, v62, v63
	v_pk_mul_f32 v[16:17], v[0:1], v[16:17] op_sel_hi:[0,1]
	v_cvt_pk_bf16_f32 v70, v16, v17
	v_lshlrev_b32_e32 v16, 16, v55
	v_and_b32_e32 v17, 0xffff0000, v55
	v_pk_mul_f32 v[16:17], v[0:1], v[16:17] op_sel_hi:[0,1]
	v_cvt_pk_bf16_f32 v71, v16, v17
	v_lshlrev_b32_e32 v16, 16, v32
	v_and_b32_e32 v17, 0xffff0000, v32
	v_pk_mul_f32 v[16:17], v[0:1], v[16:17] op_sel_hi:[0,1]
	v_cvt_pk_bf16_f32 v72, v16, v17
	v_lshlrev_b32_e32 v16, 16, v33
	v_and_b32_e32 v17, 0xffff0000, v33
	v_pk_mul_f32 v[16:17], v[0:1], v[16:17] op_sel_hi:[0,1]
	v_cvt_pk_bf16_f32 v73, v16, v17
	v_lshlrev_b32_e32 v16, 16, v34
	v_and_b32_e32 v17, 0xffff0000, v34
	v_cvt_pk_bf16_f32 v35, v38, v39
	v_pk_mul_f32 v[16:17], v[0:1], v[16:17] op_sel_hi:[0,1]
	v_cvt_pk_bf16_f32 v74, v16, v17
	v_lshlrev_b32_e32 v16, 16, v35
	v_and_b32_e32 v17, 0xffff0000, v35
	v_pk_mul_f32 v[16:17], v[0:1], v[16:17] op_sel_hi:[0,1]
	v_cvt_pk_bf16_f32 v75, v16, v17
	v_lshlrev_b32_e32 v16, 16, v36
	v_and_b32_e32 v17, 0xffff0000, v36
	v_cvt_pk_bf16_f32 v37, v42, v43
	v_pk_mul_f32 v[16:17], v[0:1], v[16:17] op_sel_hi:[0,1]
	v_cvt_pk_bf16_f32 v76, v16, v17
	v_lshlrev_b32_e32 v16, 16, v37
	v_and_b32_e32 v17, 0xffff0000, v37
	v_cvt_pk_bf16_f32 v38, v44, v45
	v_pk_mul_f32 v[16:17], v[0:1], v[16:17] op_sel_hi:[0,1]
	v_cvt_pk_bf16_f32 v77, v16, v17
	v_lshlrev_b32_e32 v16, 16, v38
	v_and_b32_e32 v17, 0xffff0000, v38
	v_cvt_pk_bf16_f32 v39, v46, v47
	v_pk_mul_f32 v[16:17], v[0:1], v[16:17] op_sel_hi:[0,1]
	v_cvt_pk_bf16_f32 v78, v16, v17
	v_lshlrev_b32_e32 v16, 16, v39
	v_and_b32_e32 v17, 0xffff0000, v39
	v_pk_mul_f32 v[16:17], v[0:1], v[16:17] op_sel_hi:[0,1]
	v_cvt_pk_bf16_f32 v79, v16, v17
	v_lshlrev_b32_e32 v16, 16, v40
	v_and_b32_e32 v17, 0xffff0000, v40
	v_cvt_pk_bf16_f32 v18, v18, v19
	v_pk_mul_f32 v[16:17], v[0:1], v[16:17] op_sel_hi:[0,1]
	v_cvt_pk_bf16_f32 v80, v16, v17
	v_lshlrev_b32_e32 v16, 16, v18
	v_and_b32_e32 v17, 0xffff0000, v18
	v_cvt_pk_bf16_f32 v19, v20, v21
	v_pk_mul_f32 v[16:17], v[0:1], v[16:17] op_sel_hi:[0,1]
	v_cvt_pk_bf16_f32 v81, v16, v17
	v_lshlrev_b32_e32 v16, 16, v19
	v_and_b32_e32 v17, 0xffff0000, v19
	v_cvt_pk_bf16_f32 v20, v22, v23
	v_pk_mul_f32 v[16:17], v[0:1], v[16:17] op_sel_hi:[0,1]
	v_cvt_pk_bf16_f32 v82, v16, v17
	v_lshlrev_b32_e32 v16, 16, v20
	v_and_b32_e32 v17, 0xffff0000, v20
	v_cvt_pk_bf16_f32 v21, v24, v25
	v_pk_mul_f32 v[16:17], v[0:1], v[16:17] op_sel_hi:[0,1]
	v_cvt_pk_bf16_f32 v83, v16, v17
	v_lshlrev_b32_e32 v16, 16, v21
	v_and_b32_e32 v17, 0xffff0000, v21
	v_cvt_pk_bf16_f32 v22, v26, v27
	v_pk_mul_f32 v[16:17], v[0:1], v[16:17] op_sel_hi:[0,1]
	v_cvt_pk_bf16_f32 v84, v16, v17
	v_lshlrev_b32_e32 v16, 16, v22
	v_and_b32_e32 v17, 0xffff0000, v22
	v_cvt_pk_bf16_f32 v23, v28, v29
; #define LAS __attribute__((address_space(3)))
; __device__ __forceinline__ unsigned cvt_pk_bf16(float lo, float hi) { f32x2 v = {lo, hi}; bf16x2_t b = __builtin_convertvector(v, bf16x2_t); return __builtin_bit_cast(unsigned, b); }
; __device__ __forceinline__ f32x16 mfma32(bf16x8 a, bf16x8 b, f32x16 c) { return __builtin_amdgcn_mfma_f32_32x32x16_bf16(a, b, c, 0, 0, 0); }
; __device__ void attn_item(const bf16_t* __restrict__ QX, const bf16_t* __restrict__ KV, bf16_t* __restrict__ O, int tt, int head, LAS unsigned char* lds) {
;     ...
;       for (int mt = 0; mt < 4; ++mt) { pf[mt][0] = scale_frag(pf[mt][0], f); pf[mt][1] = scale_frag(pf[mt][1], f); } }
; #pragma unroll
;     for (int mt = 0; mt < 4; ++mt) {
;       u32x4 p0, p1;
; #pragma unroll
;       for (int r = 0; r < 16; r += 2) {
;         const float e0 = __builtin_amdgcn_exp2f((sc[mt][r] - mx) * 1.4426950408889634f), e1 = __builtin_amdgcn_exp2f((sc[mt][r + 1] - mx) * 1.4426950408889634f);
;         sum += e0 + e1; const unsigned pk = cvt_pk_bf16(e0, e1);
;         if (r < 8) p0[r >> 1] = pk; else p1[(r - 8) >> 1] = pk;
;       }
;       pf[hf * 4 + mt][0] = (bf16x8)p0; pf[hf * 4 + mt][1] = (bf16x8)p1;
;     }
;     mxp = mx;
;   }
;   sum += __shfl_xor(sum, 32);
;   const float inv = __builtin_amdgcn_rcpf(sum);
;   __builtin_amdgcn_sched_barrier(0);
;   __syncthreads();
;   __builtin_amdgcn_sched_barrier(0);
; #pragma unroll 4
;   for (int it = 0; it < 16; ++it) { const int q = tid + it * 512, m = q >> 5, c = q & 31;
;     *(LAS u32x4*)(lds + m * VS + c * 16) = *(const u32x4*)(KV + (size_t)(mrow0 + m) * 2048 + 1024 + head * 256 + c * 8); }
;   __syncthreads();
;   __builtin_amdgcn_sched_barrier(0);
; #pragma unroll 1
;   for (int half = 0; half < 2; ++half) {
;     f32x16 acc[4];
; #pragma unroll
;     for (int i = 0; i < 4; ++i) acc[i] = (f32x16){};
;     const unsigned cofs = (unsigned)(half * 128 + 16 * G1 + 4 * p4) * 2u;
; #pragma unroll
;     for (int mt = 0; mt < 8; ++mt)
; #pragma unroll
;       for (int s = 0; s < 2; ++s) {
;         const unsigned r = (unsigned)(mt * 32 + 16 * s + 4 * h + q4);
; #pragma unroll
;         for (int et = 0; et < 4; ++et) acc[et] = mfma32(tr_frag(lds, r * VS + et * 64 + cofs, (r + 8) * VS + et * 64 + cofs), pf[mt][s], acc[et]);
	v_pk_mul_f32 v[16:17], v[0:1], v[16:17] op_sel_hi:[0,1]
	v_cvt_pk_bf16_f32 v85, v16, v17
	v_lshlrev_b32_e32 v16, 16, v23
	v_and_b32_e32 v17, 0xffff0000, v23
	v_cvt_pk_bf16_f32 v24, v30, v31
	v_pk_mul_f32 v[16:17], v[0:1], v[16:17] op_sel_hi:[0,1]
	v_cvt_pk_bf16_f32 v86, v16, v17
	v_lshlrev_b32_e32 v16, 16, v24
	v_and_b32_e32 v17, 0xffff0000, v24
	v_cvt_pk_bf16_f32 v25, v134, v135
	v_pk_mul_f32 v[16:17], v[0:1], v[16:17] op_sel_hi:[0,1]
	v_cvt_pk_bf16_f32 v87, v16, v17
	v_lshlrev_b32_e32 v16, 16, v25
	v_and_b32_e32 v17, 0xffff0000, v25
	v_cvt_pk_bf16_f32 v26, v138, v139
	v_pk_mul_f32 v[16:17], v[0:1], v[16:17] op_sel_hi:[0,1]
	v_cvt_pk_bf16_f32 v88, v16, v17
	v_lshlrev_b32_e32 v16, 16, v26
	v_and_b32_e32 v17, 0xffff0000, v26
	v_cvt_pk_bf16_f32 v27, v140, v141
	v_pk_mul_f32 v[16:17], v[0:1], v[16:17] op_sel_hi:[0,1]
	v_cvt_pk_bf16_f32 v89, v16, v17
	v_lshlrev_b32_e32 v16, 16, v27
	v_and_b32_e32 v17, 0xffff0000, v27
	v_cvt_pk_bf16_f32 v28, v142, v143
	v_pk_mul_f32 v[16:17], v[0:1], v[16:17] op_sel_hi:[0,1]
	v_cvt_pk_bf16_f32 v90, v16, v17
	v_lshlrev_b32_e32 v16, 16, v28
	v_and_b32_e32 v17, 0xffff0000, v28
	v_cvt_pk_bf16_f32 v29, v144, v145
	v_pk_mul_f32 v[16:17], v[0:1], v[16:17] op_sel_hi:[0,1]
	v_cvt_pk_bf16_f32 v91, v16, v17
	v_lshlrev_b32_e32 v16, 16, v29
	v_and_b32_e32 v17, 0xffff0000, v29
	v_cvt_pk_bf16_f32 v30, v146, v147
	v_pk_mul_f32 v[16:17], v[0:1], v[16:17] op_sel_hi:[0,1]
	v_cvt_pk_bf16_f32 v92, v16, v17
	v_lshlrev_b32_e32 v16, 16, v30
	v_and_b32_e32 v17, 0xffff0000, v30
	v_cvt_pk_bf16_f32 v31, v148, v149
	v_pk_mul_f32 v[16:17], v[0:1], v[16:17] op_sel_hi:[0,1]
	v_cvt_pk_bf16_f32 v93, v16, v17
	v_lshlrev_b32_e32 v16, 16, v31
	v_and_b32_e32 v17, 0xffff0000, v31
	v_cvt_pk_bf16_f32 v41, v150, v151
	v_pk_mul_f32 v[16:17], v[0:1], v[16:17] op_sel_hi:[0,1]
	v_cvt_pk_bf16_f32 v94, v16, v17
	v_lshlrev_b32_e32 v16, 16, v41
	v_and_b32_e32 v17, 0xffff0000, v41
	v_pk_mul_f32 v[16:17], v[0:1], v[16:17] op_sel_hi:[0,1]
	v_cvt_pk_bf16_f32 v96, v1, v2
	v_add_f32_e32 v1, v182, v137
	v_rcp_f32_e32 v128, v1
	v_cvt_pk_bf16_f32 v95, v16, v17
	v_cvt_pk_bf16_f32 v97, v3, v4
	v_cvt_pk_bf16_f32 v98, v5, v6
	v_cvt_pk_bf16_f32 v99, v7, v8
	v_cvt_pk_bf16_f32 v100, v9, v10
	v_cvt_pk_bf16_f32 v101, v11, v12
	v_cvt_pk_bf16_f32 v102, v13, v14
	v_cvt_pk_bf16_f32 v103, v15, v112
	v_cvt_pk_bf16_f32 v104, v113, v114
	v_cvt_pk_bf16_f32 v105, v115, v116
	v_cvt_pk_bf16_f32 v106, v117, v118
	v_cvt_pk_bf16_f32 v107, v119, v120
	v_cvt_pk_bf16_f32 v108, v121, v122
	v_cvt_pk_bf16_f32 v109, v123, v124
	v_cvt_pk_bf16_f32 v110, v125, v126
	v_cvt_pk_bf16_f32 v111, v127, v111
	v_cvt_pk_bf16_f32 v112, v152, v153
	v_cvt_pk_bf16_f32 v113, v154, v155
	v_cvt_pk_bf16_f32 v114, v156, v157
	v_cvt_pk_bf16_f32 v115, v158, v159
	v_cvt_pk_bf16_f32 v116, v174, v175
	v_cvt_pk_bf16_f32 v117, v176, v177
	v_cvt_pk_bf16_f32 v118, v178, v179
	v_cvt_pk_bf16_f32 v119, v180, v181
	v_cvt_pk_bf16_f32 v120, v183, v184
	v_cvt_pk_bf16_f32 v121, v185, v186
	v_cvt_pk_bf16_f32 v122, v187, v188
	v_cvt_pk_bf16_f32 v123, v189, v190
	v_cvt_pk_bf16_f32 v124, v191, v192
	v_cvt_pk_bf16_f32 v125, v193, v194
	v_cvt_pk_bf16_f32 v126, v195, v196
	v_cvt_pk_bf16_f32 v127, v197, v198
	v_bfe_u32 v0, v133, 2, 2
	v_and_b32_e32 v2, 16, v133
	s_waitcnt lgkmcnt(0)
	s_barrier
	v_lshlrev_b32_e32 v1, 2, v133
	v_and_or_b32 v132, v1, 12, v2
	v_lshl_or_b32 v2, v136, 2, v0
	v_lshlrev_b64 v[0:1], 11, v[130:131]
	v_lshl_add_u64 v[0:1], s[10:11], 0, v[0:1]
	v_lshl_add_u64 v[0:1], s[22:23], 1, v[0:1]
	v_lshl_add_u64 v[130:131], v[0:1], 0, v[160:161]
	v_mov_b32_e32 v0, 0x14400
	v_mul_u32_u24_e32 v133, 0x240, v2
	v_mad_u32_u24 v138, v2, s54, v0
	v_mov_b32_e32 v0, 0x16800
	v_mad_u32_u24 v134, v2, s54, 0
	v_or_b32_e32 v136, 0x12000, v133
	v_mad_u32_u24 v140, v2, s54, v0
	v_mad_u32_u24 v142, v2, s54, v221
	v_or_b32_e32 v144, 0x1b000, v133
	v_mad_u32_u24 v146, v2, s54, v218
	v_mad_u32_u24 v148, v2, s54, v216
	v_mad_u32_u24 v150, v2, s54, v224
	v_add_u32_e32 v135, 0xfc00, v134
	v_add_u32_e32 v137, 0, v136
	v_add_u32_e32 v139, 0, v138
	v_add_u32_e32 v141, 0, v140
	v_add_u32_e32 v143, 0, v142
	v_add_u32_e32 v145, 0, v144
	v_add_u32_e32 v147, 0, v146
	v_add_u32_e32 v149, 0, v148
	v_add_u32_e32 v151, 0, v150
	v_mov_b32_e32 v129, v128
	s_mov_b32 s20, 0
	s_mov_b64 s[22:23], -1
